# conversion load re-balanced once more: L3 gate/up tail converts 30,31; scan slices 11,13,15,22,27; R1 tail 24,23; L1 GU tail 29,17; L2 GU tail 25,26,28; prologue via streamlined converter
# baseline (speedup 1.0000x reference)
; template <int L> __device__ __forceinline__ void layer_phases(Frame& F, const int lo, const int hi, const XcdBarrier& bar, const int bid) {
;     ...
;                 if (nidle > 0) { if (ci >= 0) convert_mats(F, 22, 27, ci * NWAVES + F.wave, nidle * NWAVES); }
;                 else convert_mats(F, 22, 27, bid * NWAVES + F.wave, F.G * NWAVES);
.Lcvb_m24_done:
	s_mov_b32 s22, s23
	s_add_u32 s23, s22, 0x400
	s_cmp_ge_u32 s20, s23
	s_cbranch_scc1 .Lcvb_m23_done
	s_add_i32 s4, 0, 0x204c8
	v_mov_b32_e32 v0, s4
	ds_read_b64 v[2:3], v0
	s_waitcnt lgkmcnt(0)
	s_nop 0
	v_readfirstlane_b32 s24, v2
	v_readfirstlane_b32 s25, v3
	s_add_u32 s24, s24, 0x0
	s_addc_u32 s25, s25, 0
	s_add_u32 s28, s58, 0xdf00000
	s_addc_u32 s29, s59, 0
	s_mov_b32 s30, 0x2000
	s_mov_b32 s31, 0x1000
	s_mov_b32 s34, 0x8000000
	s_mov_b32 s35, 32
	s_mov_b32 s36, 0
	v_mul_lo_u32 v0, v183, s30
	v_lshl_add_u32 v160, v184, 4, v0
	v_add_u32_e32 v161, 0x10000, v160
	v_add_u32_e32 v162, 0x20000, v160
	v_add_u32_e32 v163, 0x30000, v160
	v_add_u32_e32 v164, 0x40000, v160
	v_add_u32_e32 v165, 0x50000, v160
	v_add_u32_e32 v166, 0x60000, v160
	v_add_u32_e32 v167, 0x70000, v160
	v_mul_lo_u32 v0, v183, s31
	v_lshl_add_u32 v168, v184, 4, v0
	v_add_u32_e32 v169, 0x8000, v168
	v_add_u32_e32 v170, 0x10000, v168
	v_add_u32_e32 v171, 0x18000, v168

; __device__ __forceinline__ void convert_mats(Frame& F, int m_lo, int m_hi, int gw, int NGW) {
;     ...
;     for (int mi = m_lo; mi < m_hi; ++mi) {
;         const MatI mt = kMats[mi]; const int cnt = (mt.Kp / 64) * (mt.Np / 64);
;         const float* src = in_ptr(F, mt.in_idx) + mt.src_off; const float* gain = mt.gain_idx >= 0 ? in_ptr(F, mt.gain_idx) + mt.gain_off : nullptr; bf16* dst = (bf16*)((unsigned char*)in_ptr(F, T_WS) + mt.dst_off);
;         while (it < base + cnt) {
.Lcsa_find:
	s_cmp_lt_u32 s67, 5
	s_cbranch_scc1 .Lcsa_setup
	s_mov_b32 s69, 0
	s_branch .Lcsa_end

.Lcsa_m3:
	s_cmp_lg_u32 s67, 3
	s_cbranch_scc1 .Lcsa_m4
	s_mov_b32 s82, 96
	s_mov_b32 s83, 0x2aaaaab
	s_mov_b32 s84, 0x6000
	s_mov_b32 s85, 0x1000
	s_mov_b32 s86, 0
	s_mov_b32 s87, 3072
	s_mov_b32 s88, 0x0
	s_mov_b32 s90, 0xc700000
	s_mov_b32 s93, 0x204b8
	s_mov_b32 s89, 0x0
	s_mov_b32 s94, 0x204b0
	s_branch .Lcsa_have

;     __device__ __forceinline__ void ids() { lane = fresh_lane(); tid = wave * 64 + lane; }
; template <int L> __device__ __forceinline__ void layer_phases(Frame& F, const int lo, const int hi, const XcdBarrier& bar, const int bid) {
;     ...
;                 } else if constexpr (L == 1) { F.ids(); convert_mats(F, 27, 29, ci * NWAVES + F.wave, nidle * NWAVES); }
.Lcvc_m29_done:
	s_mov_b32 s22, s23
	s_add_u32 s23, s22, 0x400
	s_cmp_ge_u32 s20, s23
	s_cbranch_scc1 .Lcvc_m17_done
	s_add_i32 s4, 0, 0x20508
	v_mov_b32_e32 v0, s4
	ds_read_b64 v[2:3], v0
	s_waitcnt lgkmcnt(0)
	s_nop 0
	v_readfirstlane_b32 s24, v2
	v_readfirstlane_b32 s25, v3
	s_add_u32 s24, s24, 0x1000000
	s_addc_u32 s25, s25, 0
	s_add_i32 s4, 0, 0x20500
	v_mov_b32_e32 v0, s4
	ds_read_b64 v[2:3], v0
	s_waitcnt lgkmcnt(0)
	s_nop 0
	v_readfirstlane_b32 s26, v2
	v_readfirstlane_b32 s27, v3
	s_add_u32 s26, s26, 0x2000
	s_addc_u32 s27, s27, 0
	s_add_u32 s28, s58, 0x1f700000
	s_addc_u32 s29, s59, 0
	s_mov_b32 s30, 0x2000
	s_mov_b32 s31, 0x1000
	s_mov_b32 s34, 0x8000000
	s_mov_b32 s35, 32
	s_mov_b32 s36, 0
	v_mul_lo_u32 v0, v183, s30
	v_lshl_add_u32 v160, v184, 4, v0
	v_add_u32_e32 v161, 0x10000, v160
	v_add_u32_e32 v162, 0x20000, v160
	v_add_u32_e32 v163, 0x30000, v160
	v_add_u32_e32 v164, 0x40000, v160
	v_add_u32_e32 v165, 0x50000, v160
	v_add_u32_e32 v166, 0x60000, v160
	v_add_u32_e32 v167, 0x70000, v160
	v_mul_lo_u32 v0, v183, s31
	v_lshl_add_u32 v168, v184, 4, v0
	v_add_u32_e32 v169, 0x8000, v168
	v_add_u32_e32 v170, 0x10000, v168
	v_add_u32_e32 v171, 0x18000, v168

;     __device__ __forceinline__ void ids() { lane = fresh_lane(); tid = wave * 64 + lane; }
; #define ws ((unsigned char*)in_ptr(F, T_WS))
; template <int L> __device__ __forceinline__ void layer_phases(Frame& F, const int lo, const int hi, const XcdBarrier& bar, const int bid) {
;     ...
;         {
;             const int rem = (M / 256) * (2 * FF / 256) % F.G, nidle = rem ? F.G - rem : 0, ci = bid - rem;
;             if (nidle > 0 && ci >= 0) {
;                 if constexpr (L == 0) {
;                     pg8::Gemm g2{(const bf16*)(ws + WS_PB), (const bf16*)(ws + WS_WPP), M, 4 * D, PLE, (size_t)M * PLE * 2, 8, 1 << 30};
;                     pg8::StaticOrder S2; S2.init(M, 4 * D, nidle, ci);
;                     pg8::EpiScaleBf16<false> E2{(bf16*)(ws + WS_PPO), D, nullptr, D, (size_t)M * D, nullptr};
;                     pg8::gemm_phase<pg8::EpiScaleBf16<false>, pg8::StaticOrder, false, true>(F.lds, g2, S2, E2, F.wave);
;                 } else if constexpr (L == 1) { F.ids(); convert_mats(F, 27, 29, ci * NWAVES + F.wave, nidle * NWAVES); }
;                 else if constexpr (L == 2) { F.ids(); convert_mats(F, 29, 32, ci * NWAVES + F.wave, nidle * NWAVES); }
.LBB0_3835:
	s_movk_i32 s33, 0x580
.Lt38_mod:
	s_cmp_lt_u32 s33, s52
	s_cbranch_scc1 .Lt38_mdone
	s_sub_u32 s33, s33, s52
	s_branch .Lt38_mod
.Lt38_mdone:
	s_cmp_eq_u32 s33, 0
	s_cbranch_scc1 .Lt38_all
	s_sub_u32 s3, s52, s33
	s_sub_i32 s33, s2, s33
	s_cmp_lt_i32 s33, 0
	s_cbranch_scc1 .Lt38_skip
	s_branch .Lt38_go
.Lt38_all:
	s_mov_b32 s33, s2
	s_mov_b32 s3, s52
.Lt38_go:
	v_mbcnt_lo_u32_b32 v182, -1, 0
	v_mbcnt_hi_u32_b32 v182, -1, v182
	v_lshrrev_b32_e32 v183, 3, v182
	v_and_b32_e32 v184, 7, v182
	s_lshl_b32 s4, s80, 14
	v_mul_u32_u24_e32 v0, 132, v183
	v_lshl_add_u32 v0, v184, 4, v0
	v_add_u32_e32 v172, s4, v0
	v_add_u32_e32 v173, 0x420, v172
	v_add_u32_e32 v174, 0x840, v172
	v_add_u32_e32 v175, 0xc60, v172
	v_add_u32_e32 v176, 0x1080, v172
	v_add_u32_e32 v177, 0x14a0, v172
	v_add_u32_e32 v178, 0x18c0, v172
	v_add_u32_e32 v179, 0x1ce0, v172
	v_mul_u32_u24_e32 v0, 0x420, v184
	v_lshl_add_u32 v0, v183, 2, v0
	v_add_u32_e32 v180, s4, v0
	v_lshlrev_b32_e32 v181, 2, v183
	s_lshl_b32 s20, s33, 3
	s_add_u32 s20, s20, s80
	s_lshl_b32 s21, s3, 3
	s_mov_b32 s22, 0
	s_add_i32 s4, 0, 0x20520
	v_mov_b32_e32 v0, s4
	ds_read_b64 v[2:3], v0
	s_waitcnt lgkmcnt(0)
	s_nop 0
	v_readfirstlane_b32 s58, v2
	v_readfirstlane_b32 s59, v3
	s_add_u32 s23, s22, 0xb00
	s_cmp_ge_u32 s20, s23
	s_cbranch_scc1 .Lcve_m30_done
	s_add_i32 s4, 0, 0x204f0
	v_mov_b32_e32 v0, s4
	ds_read_b64 v[2:3], v0
	s_waitcnt lgkmcnt(0)
	s_nop 0
	v_readfirstlane_b32 s24, v2
	v_readfirstlane_b32 s25, v3
	s_add_u32 s24, s24, 0x8400000
	s_addc_u32 s25, s25, 0
	s_add_u32 s28, s58, 0x1d900000
	s_addc_u32 s29, s59, 0
	s_mov_b32 s30, 0x2000
	s_mov_b32 s31, 0x2c00
	s_mov_b32 s34, 0x8000000
	s_mov_b32 s35, 32
	s_mov_b32 s36, 0
	v_mul_lo_u32 v0, v183, s30
	v_lshl_add_u32 v160, v184, 4, v0
	v_add_u32_e32 v161, 0x10000, v160
	v_add_u32_e32 v162, 0x20000, v160
	v_add_u32_e32 v163, 0x30000, v160
	v_add_u32_e32 v164, 0x40000, v160
	v_add_u32_e32 v165, 0x50000, v160
	v_add_u32_e32 v166, 0x60000, v160
	v_add_u32_e32 v167, 0x70000, v160
	v_mul_lo_u32 v0, v183, s31
	v_lshl_add_u32 v168, v184, 4, v0
	v_add_u32_e32 v169, 0x16000, v168
	v_add_u32_e32 v170, 0x2c000, v168
	v_add_u32_e32 v171, 0x42000, v168

; __device__ __forceinline__ unsigned xb_add(unsigned* p, unsigned v) { return __hip_atomic_fetch_add(p, v, __ATOMIC_RELAXED, __HIP_MEMORY_SCOPE_AGENT); }
; __device__ __forceinline__ void xcd_barrier(const XcdBarrier& b) {
;     asm volatile("s_waitcnt vmcnt(0)" ::: "memory");
;     __syncthreads();
;     if (threadIdx.x == 0) {
;         unsigned* bar = b.bar;
;         __builtin_amdgcn_s_waitcnt(0);
;         unsigned nloc = b.st[0], nx = b.st[1];
;         if (nloc == 0u) { xcd_barrier_complete(bar, b.x, nloc, nx); b.st[0] = nloc; b.st[1] = nx; }
;         const unsigned old = xb_add(&bar[XB_XSUB(b.x)], 1u);
;         const unsigned gen = old / nloc;
;         if (old + 1u == (gen + 1u) * nloc) {
;             __builtin_amdgcn_fence(__ATOMIC_RELEASE, "agent");
;             asm volatile("s_waitcnt vmcnt(0)" ::: "memory");
;             const unsigned og = xb_add(&bar[XB_TOP], 1u);
.Lcve_m31_done:
	s_mov_b32 s22, s23
	s_waitcnt vmcnt(0)
.Lt38_skip:
	s_add_i32 s0, 0, 0x20520
	v_mov_b32_e32 v0, s0
	ds_read_b64 v[0:1], v0
	s_getreg_b32 s3, hwreg(HW_REG_XCC_ID, 0, 4)
	s_waitcnt vmcnt(0)
	s_waitcnt vmcnt(16) lgkmcnt(0)
	s_barrier
	v_readfirstlane_b32 s4, v0
	v_readfirstlane_b32 s5, v1
	s_mov_b64 s[0:1], exec
	v_readlane_b32 s6, v246, 2
	v_readlane_b32 s7, v246, 3
	s_and_b64 s[6:7], s[0:1], s[6:7]
	s_mov_b64 exec, s[6:7]
	s_cbranch_execz .LBB0_3887
	s_add_i32 s6, 0, 0x20160
	v_mov_b32_e32 v0, s6
	s_waitcnt vmcnt(0) expcnt(0) lgkmcnt(0)
	ds_read_b32 v2, v0
	s_add_i32 s6, 0, 0x20164
	v_mov_b32_e32 v0, s6
	ds_read_b32 v0, v0
	s_and_b32 s3, s3, 15
	s_waitcnt lgkmcnt(1)
	v_cmp_ne_u32_e32 vcc, 0, v2
	s_cbranch_vccnz .LBB0_3851
	v_readlane_b32 s6, v246, 0
	v_readlane_b32 s7, v246, 1
	s_load_dwordx2 s[10:11], s[6:7], 0x4
	s_add_u32 s6, s4, 0x4200
	s_addc_u32 s7, s5, 0
	s_add_u32 s8, s4, 0x4400
	s_addc_u32 s9, s5, 0
	s_waitcnt lgkmcnt(0)
	s_mul_i32 s33, s10, s52
	s_add_u32 s10, s4, 0x4500
	s_mul_i32 s33, s33, s11
	s_addc_u32 s11, s5, 0
	s_add_u32 s12, s4, 0x4600
	s_addc_u32 s13, s5, 0
	s_add_u32 s14, s4, 0x4700
	s_addc_u32 s15, s5, 0
	s_add_u32 s16, s4, 0x4800
	s_addc_u32 s17, s5, 0
	s_add_u32 s18, s4, 0x4900
	s_addc_u32 s19, s5, 0
	s_add_u32 s20, s4, 0x4a00
	s_addc_u32 s21, s5, 0
	s_add_u32 s22, s4, 0x4b00
	s_addc_u32 s23, s5, 0
	s_add_u32 s24, s4, 0x4c00
	s_addc_u32 s25, s5, 0
	s_add_u32 s26, s4, 0x4d00
	s_addc_u32 s27, s5, 0
	s_add_u32 s28, s4, 0x4e00
	s_addc_u32 s29, s5, 0
	s_add_u32 s30, s4, 0x4f00
	s_addc_u32 s31, s5, 0
	s_add_u32 s36, s4, 0x5000
	s_addc_u32 s37, s5, 0
	s_add_u32 s38, s4, 0x5100
	s_addc_u32 s39, s5, 0
	s_add_u32 s40, s4, 0x5200
	s_addc_u32 s41, s5, 0
	s_add_u32 s42, s4, 0x5300
	s_addc_u32 s43, s5, 0
	s_mov_b32 s34, 1
	v_mov_b32_e32 v16, 0
	s_branch .LBB0_3839
